# LayerNorm phases: the 16 row loads of each iteration are prefetched one iteration ahead into a register buffer (the compiler waited after every 4 loads)
# baseline (speedup 1.0000x reference)
; DI int otid() { int t = threadIdx.x; asm volatile("" : "+v"(t)); return t; }
; DI float bflo(unsigned w) { return __uint_as_float(w << 16); }
; DI float bfhi(unsigned w) { return __uint_as_float(w & 0xffff0000u); }
; DI void phase_ln(const bf16_t* vin, float* xf, bf16_t* xb, const float* g, const float* b, bool write_f32) {
;     const int tid = otid(), wave = tid >> 6, lane = tid & 63;
;     f32x4 gv[4], bv[4];
; #pragma unroll
;     for (int i = 0; i < 4; ++i) { gv[i] = *(const f32x4*)(g + i * 256 + lane * 4); bv[i] = *(const f32x4*)(b + i * 256 + lane * 4); }
;     const int nw = gridDim.x * 8;
;     constexpr int R = 4;
;     for (int r0 = blockIdx.x * 8 + wave; r0 < T_; r0 += nw * R) {
;         f32x4 v[R][4];
; #pragma unroll
;         for (int k = 0; k < R; ++k) {
;             const bf16_t* row = vin + (size_t)(r0 + k * nw) * D_;
; #pragma unroll
;             for (int i = 0; i < 4; ++i) { const u32x2 w = *(const u32x2*)(row + i * 256 + lane * 4); v[k][i] = (f32x4){bflo(w.x), bfhi(w.x), bflo(w.y), bfhi(w.y)}; }
;         }
.LBB0_565:
	s_nop 0
	v_readlane_b32 s2, v255, 61
	v_readlane_b32 s3, v255, 62
	s_and_b64 vcc, exec, s[2:3]
	s_cbranch_vccz .LBB0_575
	v_readlane_b32 s0, v255, 56
	v_mov_b32_e32 v33, v163
	s_cmp_eq_u32 s0, 2
	v_readlane_b32 s2, v255, 54
	v_readlane_b32 s4, v254, 49
	v_ashrrev_i32_e32 v40, 6, v33
	s_cselect_b64 s[0:1], -1, 0
	v_readlane_b32 s3, v255, 55
	v_add_u32_e32 v32, s4, v40
	s_mov_b32 s4, 0x10000
	s_and_b64 s[2:3], s[2:3], s[0:1]
	v_cmp_gt_i32_e32 vcc, s4, v32
	s_and_saveexec_b64 s[4:5], vcc
	v_readlane_b32 s14, v254, 53
	v_readlane_b32 s15, v254, 54
	s_mov_b32 s16, 0x6000000
	s_mov_b32 s18, 0x3a800000
	s_cbranch_execz .LBB0_569
	v_readlane_b32 s6, v255, 54
	v_readlane_b32 s7, v255, 55
	s_and_b64 s[6:7], s[6:7], exec
	s_cselect_b32 s6, 0x3000, 0
	v_readlane_b32 s72, v253, 39
	v_readlane_b32 s73, v253, 40
	s_add_u32 s10, s72, s6
	v_readlane_b32 s74, v253, 41
	s_addc_u32 s11, s73, 0
	v_readlane_b32 s75, v253, 42
	s_add_u32 s12, s74, s6
	s_addc_u32 s13, s75, 0
	v_readlane_b32 s6, v255, 56
	s_cmp_eq_u32 s6, 6
	s_cselect_b64 s[6:7], -1, 0
	s_and_b64 s[8:9], s[6:7], exec
	s_movk_i32 s8, 0x800
	s_cselect_b32 s8, 0x400, s8
	s_and_b64 s[0:1], s[0:1], exec
	s_cselect_b32 s0, 0, s8
	s_lshl_b32 s8, s0, 2
	s_add_u32 s0, s10, s8
	v_lshlrev_b32_e32 v0, 2, v33
	s_addc_u32 s1, s11, 0
	v_and_b32_e32 v34, 0xfc, v0
	s_add_u32 s8, s12, s8
	v_lshlrev_b32_e32 v28, 2, v34
	s_addc_u32 s9, s13, 0
	global_load_dwordx4 v[0:3], v28, s[0:1]
	global_load_dwordx4 v[4:7], v28, s[0:1] offset:1024
	global_load_dwordx4 v[8:11], v28, s[8:9]
	global_load_dwordx4 v[12:15], v28, s[8:9] offset:1024
	global_load_dwordx4 v[16:19], v28, s[0:1] offset:2048
	global_load_dwordx4 v[20:23], v28, s[0:1] offset:3072
	global_load_dwordx4 v[24:27], v28, s[8:9] offset:2048
	s_nop 0
	global_load_dwordx4 v[28:31], v28, s[8:9] offset:3072
	s_or_b64 s[0:1], s[6:7], s[2:3]
	s_and_b64 s[0:1], s[0:1], exec
	v_readlane_b32 s8, v253, 0
	v_readlane_b32 s11, v253, 3
	v_readlane_b32 s0, v253, 9
	v_readlane_b32 s10, v253, 2
	s_cselect_b32 s1, s11, s0
	v_readlane_b32 s0, v253, 8
	v_readlane_b32 s6, v254, 50
	s_cselect_b32 s0, s10, s0
	v_lshlrev_b32_e32 v136, 1, v34
	v_and_b32_e32 v33, 63, v33
	v_add_u32_e32 v40, s6, v40
	v_lshl_add_u64 v[34:35], s[0:1], 0, v[136:137]
	v_lshl_add_u64 v[36:37], s[94:95], 0, v[136:137]
	v_lshlrev_b32_e32 v136, 3, v33
	v_ashrrev_i32_e32 v33, 31, v32
	v_ashrrev_i32_e32 v41, 31, v40
	v_lshlrev_b64 v[44:45], 11, v[32:33]
	v_lshlrev_b64 v[42:43], 11, v[40:41]
	s_movk_i32 s37, 0x90
	v_lshl_add_u64 v[38:39], s[88:89], 0, v[44:45]
	v_lshl_add_u64 v[40:41], s[0:1], 0, v[42:43]
	v_lshl_add_u64 v[42:43], s[88:89], 0, v[42:43]
	v_lshl_add_u64 v[44:45], s[0:1], 0, v[44:45]
	s_mov_b64 s[6:7], 0
	v_readlane_b32 s76, v253, 43
	v_readlane_b32 s77, v253, 44
	v_readlane_b32 s78, v253, 45
	v_readlane_b32 s79, v253, 46
	v_readlane_b32 s80, v253, 47
	v_readlane_b32 s81, v253, 48
	v_readlane_b32 s82, v253, 49
	v_readlane_b32 s83, v253, 50
	v_readlane_b32 s84, v253, 51
	v_readlane_b32 s85, v253, 52
	v_readlane_b32 s86, v253, 53
	v_readlane_b32 s87, v253, 54
	v_readlane_b32 s9, v253, 1
	v_lshl_add_u64 v[240:241], v[44:45], 0, v[136:137]
	v_mov_b32_e32 v244, 0x400000
	v_mov_b32_e32 v245, 0
	s_mov_b32 s32, 0
	v_mov_b64_e32 v[242:243], v[240:241]
	global_load_dwordx2 v[176:177], v[242:243], off
	global_load_dwordx2 v[178:179], v[242:243], off offset:512
	global_load_dwordx2 v[180:181], v[242:243], off offset:1024
	global_load_dwordx2 v[182:183], v[242:243], off offset:1536
	v_lshl_add_u64 v[242:243], v[242:243], 0, v[244:245]
	global_load_dwordx2 v[184:185], v[242:243], off
	global_load_dwordx2 v[186:187], v[242:243], off offset:512
	global_load_dwordx2 v[188:189], v[242:243], off offset:1024
	global_load_dwordx2 v[190:191], v[242:243], off offset:1536
	v_lshl_add_u64 v[242:243], v[242:243], 0, v[244:245]
	global_load_dwordx2 v[192:193], v[242:243], off
	global_load_dwordx2 v[194:195], v[242:243], off offset:512
	global_load_dwordx2 v[196:197], v[242:243], off offset:1024
	global_load_dwordx2 v[198:199], v[242:243], off offset:1536
	v_lshl_add_u64 v[242:243], v[242:243], 0, v[244:245]
	global_load_dwordx2 v[200:201], v[242:243], off
	global_load_dwordx2 v[202:203], v[242:243], off offset:512
	global_load_dwordx2 v[204:205], v[242:243], off offset:1024
	global_load_dwordx2 v[206:207], v[242:243], off offset:1536
	v_lshl_add_u64 v[242:243], v[242:243], 0, v[244:245]
	v_mov_b64_e32 v[240:241], v[242:243]
	s_waitcnt vmcnt(0)
.LBB0_568:
	s_waitcnt vmcnt(16)
	v_mov_b64_e32 v[208:209], v[176:177]
	v_mov_b64_e32 v[210:211], v[178:179]
	v_mov_b64_e32 v[212:213], v[180:181]
	v_mov_b64_e32 v[214:215], v[182:183]
	v_mov_b64_e32 v[216:217], v[184:185]
	v_mov_b64_e32 v[218:219], v[186:187]
	v_mov_b64_e32 v[220:221], v[188:189]
	v_mov_b64_e32 v[222:223], v[190:191]
	v_mov_b64_e32 v[224:225], v[192:193]
	v_mov_b64_e32 v[226:227], v[194:195]
	v_mov_b64_e32 v[228:229], v[196:197]
	v_mov_b64_e32 v[230:231], v[198:199]
	v_mov_b64_e32 v[232:233], v[200:201]
	v_mov_b64_e32 v[234:235], v[202:203]
	v_mov_b64_e32 v[236:237], v[204:205]
	v_mov_b64_e32 v[238:239], v[206:207]
	s_add_i32 s32, s32, 1
	s_cmp_ge_u32 s32, 8
	s_cbranch_scc1 .Lln_nopf
	v_mov_b64_e32 v[242:243], v[240:241]
	global_load_dwordx2 v[176:177], v[242:243], off
	global_load_dwordx2 v[178:179], v[242:243], off offset:512
	global_load_dwordx2 v[180:181], v[242:243], off offset:1024
	global_load_dwordx2 v[182:183], v[242:243], off offset:1536
	v_lshl_add_u64 v[242:243], v[242:243], 0, v[244:245]
	global_load_dwordx2 v[184:185], v[242:243], off
	global_load_dwordx2 v[186:187], v[242:243], off offset:512
	global_load_dwordx2 v[188:189], v[242:243], off offset:1024
	global_load_dwordx2 v[190:191], v[242:243], off offset:1536
	v_lshl_add_u64 v[242:243], v[242:243], 0, v[244:245]
	global_load_dwordx2 v[192:193], v[242:243], off
	global_load_dwordx2 v[194:195], v[242:243], off offset:512
	global_load_dwordx2 v[196:197], v[242:243], off offset:1024
	global_load_dwordx2 v[198:199], v[242:243], off offset:1536
	v_lshl_add_u64 v[242:243], v[242:243], 0, v[244:245]
	global_load_dwordx2 v[200:201], v[242:243], off
	global_load_dwordx2 v[202:203], v[242:243], off offset:512
	global_load_dwordx2 v[204:205], v[242:243], off offset:1024
	global_load_dwordx2 v[206:207], v[242:243], off offset:1536
	v_lshl_add_u64 v[242:243], v[242:243], 0, v[244:245]
	v_mov_b64_e32 v[240:241], v[242:243]
; DI float bflo(unsigned w) { return __uint_as_float(w << 16); }
; DI float bfhi(unsigned w) { return __uint_as_float(w & 0xffff0000u); }
; DI float wave_sum(float v) { v = row16_sum(v); return (rdlane(v, 0) + rdlane(v, 16)) + (rdlane(v, 32) + rdlane(v, 48)); }
; DI void phase_ln(const bf16_t* vin, float* xf, bf16_t* xb, const float* g, const float* b, bool write_f32) {
;     ...
;             const bf16_t* row = vin + (size_t)(r0 + k * nw) * D_;
; #pragma unroll
;             for (int i = 0; i < 4; ++i) { const u32x2 w = *(const u32x2*)(row + i * 256 + lane * 4); v[k][i] = (f32x4){bflo(w.x), bfhi(w.x), bflo(w.y), bfhi(w.y)}; }
;         }
; #pragma unroll
;         for (int k = 0; k < R; ++k) {
;             float s = 0.f;
; #pragma unroll
;             for (int i = 0; i < 4; ++i) s += (v[k][i][0] + v[k][i][1]) + (v[k][i][2] + v[k][i][3]);
;             const float mean = wave_sum(s) * (1.0f / 1024.0f);
;             float q = 0.f;
; #pragma unroll
;             for (int i = 0; i < 4; ++i) { const f32x4 d = v[k][i] - mean; q += (d[0] * d[0] + d[1] * d[1]) + (d[2] * d[2] + d[3] * d[3]); }
.Lln_nopf:
	v_lshl_add_u64 v[46:47], v[44:45], 0, v[136:137]
	v_mov_b64_e32 v[110:111], v[208:209]
	v_mov_b64_e32 v[112:113], v[210:211]
	v_mov_b64_e32 v[48:49], v[212:213]
	s_mul_i32 s0, s50, 24
	v_mov_b64_e32 v[46:47], v[214:215]
	v_lshl_add_u64 v[126:127], v[38:39], 0, v[136:137]
	v_lshl_add_u64 v[38:39], v[38:39], 0, s[14:15]
	v_lshl_add_u64 v[44:45], v[44:45], 0, s[14:15]
	v_lshlrev_b32_e32 v119, 16, v111
	v_lshlrev_b32_e32 v118, 16, v110
	v_lshlrev_b32_e32 v104, 16, v48
	v_and_b32_e32 v105, 0xffff0000, v48
	v_lshlrev_b32_e32 v103, 16, v46
	v_and_b32_e32 v99, 0xffff0000, v46
	v_lshlrev_b32_e32 v101, 16, v47
	v_and_b32_e32 v97, 0xffff0000, v47
	v_lshl_add_u64 v[46:47], v[40:41], 0, v[136:137]
	v_lshlrev_b32_e32 v106, 16, v49
	v_and_b32_e32 v107, 0xffff0000, v49
	v_mov_b64_e32 v[108:109], v[216:217]
	v_mov_b64_e32 v[94:95], v[218:219]
	v_mov_b64_e32 v[48:49], v[220:221]
	v_and_b32_e32 v111, 0xffff0000, v111
	v_mov_b64_e32 v[46:47], v[222:223]
	v_and_b32_e32 v110, 0xffff0000, v110
	v_pk_add_f32 v[114:115], v[118:119], v[110:111]
	v_lshlrev_b32_e32 v117, 16, v113
	v_lshlrev_b32_e32 v116, 16, v112
	v_and_b32_e32 v113, 0xffff0000, v113
	v_and_b32_e32 v112, 0xffff0000, v112
	v_add_f32_e32 v33, v114, v115
	v_pk_add_f32 v[114:115], v[116:117], v[112:113]
	v_add_f32_e32 v102, 0, v33
	v_pk_add_f32 v[114:115], v[114:115], v[114:115] op_sel:[0,1] op_sel_hi:[1,0]
	v_add_f32_e32 v100, v104, v105
	v_add_f32_e32 v96, v106, v107
	v_mov_b32_e32 v115, v99
	v_pk_add_f32 v[114:115], v[102:103], v[114:115]
	v_pk_add_f32 v[120:121], v[100:101], v[96:97]
	v_lshl_add_u64 v[40:41], v[40:41], 0, s[14:15]
	v_pk_add_f32 v[114:115], v[114:115], v[120:121]
	v_lshlrev_b32_e32 v86, 16, v48
	v_and_b32_e32 v87, 0xffff0000, v48
	v_lshlrev_b32_e32 v85, 16, v46
	v_and_b32_e32 v81, 0xffff0000, v46
	v_add_u32_e32 v46, s34, v32
	v_lshlrev_b32_e32 v83, 16, v47
	v_and_b32_e32 v79, 0xffff0000, v47
	v_ashrrev_i32_e32 v47, 31, v46
	v_lshlrev_b64 v[72:73], 11, v[46:47]
	v_lshl_add_u64 v[46:47], v[34:35], 0, v[72:73]
	v_lshlrev_b32_e32 v88, 16, v49
	v_and_b32_e32 v89, 0xffff0000, v49
	v_mov_b64_e32 v[92:93], v[224:225]
	v_mov_b64_e32 v[90:91], v[226:227]
	v_mov_b64_e32 v[48:49], v[228:229]
	v_add_f32_e32 v33, v114, v115
	v_mov_b64_e32 v[46:47], v[230:231]
	v_add_f32_e32 v82, v86, v87
	v_add_f32_dpp v33, v33, v33 quad_perm:[1,0,3,2] row_mask:0xf bank_mask:0xf bound_ctrl:1
	v_add_f32_e32 v78, v88, v89
	v_pk_add_f32 v[128:129], v[82:83], v[78:79]
	v_add_f32_dpp v33, v33, v33 quad_perm:[2,3,0,1] row_mask:0xf bank_mask:0xf bound_ctrl:1
	v_lshl_add_u64 v[72:73], v[36:37], 0, v[72:73]
	v_lshlrev_b32_e32 v68, 16, v48
	v_and_b32_e32 v69, 0xffff0000, v48
	v_lshlrev_b32_e32 v67, 16, v46
	v_and_b32_e32 v63, 0xffff0000, v46
	v_add_u32_e32 v46, s0, v32
	v_lshlrev_b32_e32 v65, 16, v47
	v_and_b32_e32 v61, 0xffff0000, v47
	v_ashrrev_i32_e32 v47, 31, v46
	v_lshlrev_b64 v[58:59], 11, v[46:47]
	v_lshl_add_u64 v[46:47], v[34:35], 0, v[58:59]
	v_lshlrev_b32_e32 v70, 16, v49
	v_and_b32_e32 v71, 0xffff0000, v49
	v_mov_b64_e32 v[76:77], v[232:233]
	v_mov_b64_e32 v[74:75], v[234:235]
	v_mov_b64_e32 v[48:49], v[236:237]
	v_add_f32_dpp v33, v33, v33 row_half_mirror row_mask:0xf bank_mask:0xf bound_ctrl:1
	v_mov_b64_e32 v[46:47], v[238:239]
	v_add_f32_e32 v64, v68, v69
	v_add_f32_dpp v33, v33, v33 row_mirror row_mask:0xf bank_mask:0xf bound_ctrl:1
	v_add_f32_e32 v60, v70, v71
	v_readlane_b32 s8, v33, 16
	v_readlane_b32 s9, v33, 48
	v_readlane_b32 s0, v33, 0
	v_readlane_b32 s1, v33, 32
	v_mov_b32_e32 v114, s8
	v_mov_b32_e32 v115, s9
	v_pk_add_f32 v[114:115], s[0:1], v[114:115]
	v_lshl_add_u64 v[58:59], v[36:37], 0, v[58:59]
	v_add_f32_e32 v33, v114, v115
	v_fmac_f32_e32 v110, 0xba800000, v33
	v_fmac_f32_e32 v111, 0xba800000, v33
	v_fmac_f32_e32 v119, 0xba800000, v33
	v_fmac_f32_e32 v118, 0xba800000, v33
	v_mov_b32_e32 v122, v119
	v_mov_b32_e32 v123, v111
	v_mov_b32_e32 v119, v110
	v_pk_mul_f32 v[114:115], v[122:123], v[122:123]
	v_pk_mul_f32 v[110:111], v[118:119], v[118:119]
	v_fmac_f32_e32 v112, 0xba800000, v33
	v_pk_mov_b32 v[120:121], v[110:111], v[114:115] op_sel:[1,0]
	v_mov_b32_e32 v111, v115
	v_fmac_f32_e32 v113, 0xba800000, v33
	v_fmac_f32_e32 v117, 0xba800000, v33
	v_pk_add_f32 v[110:111], v[120:121], v[110:111]
	v_fmac_f32_e32 v116, 0xba800000, v33
	v_mov_b32_e32 v120, v117
	v_mov_b32_e32 v121, v113
	v_mov_b32_e32 v117, v112
	v_pk_mul_f32 v[114:115], v[120:121], v[120:121]
	v_pk_mul_f32 v[112:113], v[116:117], v[116:117]
	v_fmac_f32_e32 v104, 0xba800000, v33
	v_pk_mov_b32 v[124:125], v[112:113], v[114:115] op_sel:[1,0]
	v_mov_b32_e32 v113, v115
	v_fmac_f32_e32 v105, 0xba800000, v33
	v_fmac_f32_e32 v106, 0xba800000, v33
	v_pk_add_f32 v[112:113], v[124:125], v[112:113]
	v_fmac_f32_e32 v107, 0xba800000, v33
	v_pk_add_f32 v[110:111], v[110:111], v[110:111] op_sel_hi:[0,1]
	v_pk_add_f32 v[112:113], v[112:113], v[112:113] op_sel_hi:[0,1]
	v_fmac_f32_e32 v97, 0xba800000, v33
	v_fmac_f32_e32 v101, 0xba800000, v33
	v_fmac_f32_e32 v99, 0xba800000, v33
	v_fmac_f32_e32 v103, 0xba800000, v33
	v_mul_f32_e32 v110, v101, v101
	v_mul_f32_e32 v112, v97, v97
	v_pk_add_f32 v[110:111], v[110:111], v[112:113]
	v_and_b32_e32 v113, 0xffff0000, v109
	v_and_b32_e32 v112, 0xffff0000, v108
	v_mov_b32_e32 v98, v103
	v_mov_b32_e32 v96, v101
	v_add_u32_e32 v32, s54, v32
	v_lshlrev_b32_e32 v56, 16, v49
	v_and_b32_e32 v57, 0xffff0000, v49
	v_lshlrev_b32_e32 v53, 16, v46
	v_and_b32_e32 v49, 0xffff0000, v46
	v_lshlrev_b32_e32 v51, 16, v47
	v_and_b32_e32 v47, 0xffff0000, v47
	v_mul_f32_e32 v46, v104, v104
	v_pk_fma_f32 v[114:115], v[104:105], v[104:105], v[46:47] op_sel_hi:[1,1,0]
	v_mul_f32_e32 v46, v106, v106
; DI float wave_sum(float v) { v = row16_sum(v); return (rdlane(v, 0) + rdlane(v, 16)) + (rdlane(v, 32) + rdlane(v, 48)); }
; DI void phase_ln(const bf16_t* vin, float* xf, bf16_t* xb, const float* g, const float* b, bool write_f32) {
;     ...
;             for (int i = 0; i < 4; ++i) s += (v[k][i][0] + v[k][i][1]) + (v[k][i][2] + v[k][i][3]);
;             const float mean = wave_sum(s) * (1.0f / 1024.0f);
;             float q = 0.f;
; #pragma unroll
;             for (int i = 0; i < 4; ++i) { const f32x4 d = v[k][i] - mean; q += (d[0] * d[0] + d[1] * d[1]) + (d[2] * d[2] + d[3] * d[3]); }
;             const float rstd = rsqrtf(wave_sum(q) * (1.0f / 1024.0f) + 1e-5f);
	v_pk_fma_f32 v[124:125], v[106:107], v[106:107], v[46:47] op_sel_hi:[1,1,0]
	v_mul_f32_e32 v114, v103, v103
	v_mul_f32_e32 v124, v99, v99
	v_pk_add_f32 v[114:115], v[114:115], v[124:125]
	v_lshlrev_b32_e32 v54, 16, v48
	v_pk_add_f32 v[110:111], v[114:115], v[110:111]
	v_and_b32_e32 v55, 0xffff0000, v48
	v_add_f32_e32 v33, v110, v111
	v_add_f32_e32 v50, v54, v55
	s_nop 0
	v_add_f32_dpp v33, v33, v33 quad_perm:[1,0,3,2] row_mask:0xf bank_mask:0xf bound_ctrl:1
	s_nop 1
	v_add_f32_dpp v33, v33, v33 quad_perm:[2,3,0,1] row_mask:0xf bank_mask:0xf bound_ctrl:1
	s_nop 1
	v_add_f32_dpp v33, v33, v33 row_half_mirror row_mask:0xf bank_mask:0xf bound_ctrl:1
	s_nop 1
	v_add_f32_dpp v33, v33, v33 row_mirror row_mask:0xf bank_mask:0xf bound_ctrl:1
	s_nop 0
	v_readlane_b32 s8, v33, 16
	v_readlane_b32 s9, v33, 48
	v_readlane_b32 s0, v33, 0
	v_readlane_b32 s1, v33, 32
	v_mov_b32_e32 v110, s8
	v_mov_b32_e32 v111, s9
	v_pk_add_f32 v[124:125], s[0:1], v[110:111]
	v_lshlrev_b32_e32 v111, 16, v109
	v_lshlrev_b32_e32 v110, 16, v108
	v_pk_add_f32 v[108:109], v[110:111], v[112:113]
	s_nop 0
	v_add_f32_e32 v33, v108, v109
	v_lshlrev_b32_e32 v109, 16, v95
	v_lshlrev_b32_e32 v108, 16, v94
	v_and_b32_e32 v95, 0xffff0000, v95
	v_and_b32_e32 v94, 0xffff0000, v94
	v_pk_add_f32 v[114:115], v[108:109], v[94:95]
	v_add_f32_e32 v84, 0, v33
	v_pk_add_f32 v[114:115], v[114:115], v[114:115] op_sel:[0,1] op_sel_hi:[1,0]
	s_nop 0
	v_mov_b32_e32 v115, v81
	v_pk_add_f32 v[114:115], v[84:85], v[114:115]
	v_and_b32_e32 v84, 0xffff0000, v90
	v_pk_add_f32 v[114:115], v[114:115], v[128:129]
	s_nop 0
	v_add_f32_e32 v33, v114, v115
	s_nop 1
	v_add_f32_dpp v33, v33, v33 quad_perm:[1,0,3,2] row_mask:0xf bank_mask:0xf bound_ctrl:1
	s_nop 1
	v_add_f32_dpp v33, v33, v33 quad_perm:[2,3,0,1] row_mask:0xf bank_mask:0xf bound_ctrl:1
	s_nop 1
	v_add_f32_dpp v33, v33, v33 row_half_mirror row_mask:0xf bank_mask:0xf bound_ctrl:1
	s_nop 1
	v_add_f32_dpp v33, v33, v33 row_mirror row_mask:0xf bank_mask:0xf bound_ctrl:1
	s_nop 0
	v_readlane_b32 s8, v33, 16
	v_readlane_b32 s9, v33, 48
	v_readlane_b32 s0, v33, 0
	v_readlane_b32 s1, v33, 32
	v_mov_b32_e32 v114, s8
	v_mov_b32_e32 v115, s9
	v_pk_add_f32 v[114:115], s[0:1], v[114:115]
	s_nop 0
	v_add_f32_e32 v33, v114, v115
	v_fmac_f32_e32 v112, 0xba800000, v33
	v_fmac_f32_e32 v113, 0xba800000, v33
	v_fmac_f32_e32 v111, 0xba800000, v33
	v_fmac_f32_e32 v110, 0xba800000, v33
	v_mov_b32_e32 v114, v111
	v_mov_b32_e32 v115, v113
	v_mov_b32_e32 v111, v112
	v_pk_mul_f32 v[128:129], v[114:115], v[114:115]
	v_pk_mul_f32 v[112:113], v[110:111], v[110:111]
	v_fmac_f32_e32 v94, 0xba800000, v33
	v_pk_mov_b32 v[130:131], v[112:113], v[128:129] op_sel:[1,0]
	v_mov_b32_e32 v113, v129
	v_pk_add_f32 v[112:113], v[130:131], v[112:113]
	v_fmac_f32_e32 v95, 0xba800000, v33
	v_fmac_f32_e32 v109, 0xba800000, v33
	v_pk_add_f32 v[128:129], v[112:113], v[112:113] op_sel_hi:[0,1]
	v_fmac_f32_e32 v108, 0xba800000, v33
	v_mov_b32_e32 v112, v109
	v_mov_b32_e32 v113, v95
	v_mov_b32_e32 v109, v94
	v_pk_mul_f32 v[130:131], v[112:113], v[112:113]
	v_pk_mul_f32 v[94:95], v[108:109], v[108:109]
	v_fmac_f32_e32 v86, 0xba800000, v33
	v_pk_mov_b32 v[132:133], v[94:95], v[130:131] op_sel:[1,0]
	v_mov_b32_e32 v95, v131
	v_fmac_f32_e32 v87, 0xba800000, v33
	v_fmac_f32_e32 v88, 0xba800000, v33
	v_mul_f32_e32 v46, v86, v86
	v_pk_add_f32 v[94:95], v[132:133], v[94:95]
	v_fmac_f32_e32 v89, 0xba800000, v33
	v_pk_fma_f32 v[130:131], v[86:87], v[86:87], v[46:47] op_sel_hi:[1,1,0]
	v_mul_f32_e32 v46, v88, v88
	v_pk_add_f32 v[94:95], v[94:95], v[94:95] op_sel_hi:[0,1]
	v_pk_fma_f32 v[132:133], v[88:89], v[88:89], v[46:47] op_sel_hi:[1,1,0]
	v_fmac_f32_e32 v79, 0xba800000, v33
	v_fmac_f32_e32 v83, 0xba800000, v33
	v_fmac_f32_e32 v81, 0xba800000, v33
	v_fmac_f32_e32 v85, 0xba800000, v33
	v_mul_f32_e32 v130, v85, v85
	v_mul_f32_e32 v132, v81, v81
	v_mul_f32_e32 v128, v83, v83
	v_mul_f32_e32 v94, v79, v79
	v_pk_add_f32 v[130:131], v[130:131], v[132:133]
	v_pk_add_f32 v[94:95], v[128:129], v[94:95]
	v_mov_b32_e32 v129, v124
	v_pk_add_f32 v[94:95], v[130:131], v[94:95]
	v_mov_b32_e32 v80, v85
	v_add_f32_e32 v33, v94, v95
	v_mov_b32_e32 v78, v83
	v_and_b32_e32 v85, 0xffff0000, v91
	v_add_f32_dpp v33, v33, v33 quad_perm:[1,0,3,2] row_mask:0xf bank_mask:0xf bound_ctrl:1
	s_nop 1
	v_add_f32_dpp v33, v33, v33 quad_perm:[2,3,0,1] row_mask:0xf bank_mask:0xf bound_ctrl:1
	s_nop 1
	v_add_f32_dpp v33, v33, v33 row_half_mirror row_mask:0xf bank_mask:0xf bound_ctrl:1
	s_nop 1
	v_add_f32_dpp v33, v33, v33 row_mirror row_mask:0xf bank_mask:0xf bound_ctrl:1
	s_nop 0
	v_readlane_b32 s8, v33, 16
	v_readlane_b32 s9, v33, 48
	v_readlane_b32 s0, v33, 0
	v_readlane_b32 s1, v33, 32
	v_mov_b32_e32 v94, s8
	v_mov_b32_e32 v95, s9
	v_pk_add_f32 v[94:95], s[0:1], v[94:95]
	s_mov_b32 s0, 0x3727c5ac
	v_mov_b32_e32 v128, v94
	v_mov_b32_e32 v124, v95
	v_pk_add_f32 v[124:125], v[128:129], v[124:125]
	v_mov_b64_e32 v[94:95], s[0:1]
	v_pk_fma_f32 v[124:125], v[124:125], s[18:19], v[94:95] op_sel_hi:[1,0,0]
	s_nop 0
	v_mul_f32_e32 v33, 0x4b800000, v125
	v_cmp_gt_f32_e64 s[0:1], s44, v125
	v_cmp_gt_f32_e32 vcc, s44, v124
	s_nop 0
	v_cndmask_b32_e64 v33, v125, v33, s[0:1]
	v_rsq_f32_e32 v33, v33
	s_nop 0
	v_mul_f32_e32 v46, 0x45800000, v33
	v_cndmask_b32_e64 v46, v33, v46, s[0:1]
	v_pk_mul_f32 v[118:119], v[118:119], v[46:47] op_sel_hi:[1,0]
	v_pk_mul_f32 v[122:123], v[122:123], v[46:47] op_sel_hi:[1,0]
	v_pk_fma_f32 v[118:119], v[0:1], v[118:119], v[8:9]
	v_pk_fma_f32 v[122:123], v[2:3], v[122:123], v[10:11]
	v_bfe_u32 v33, v118, 16, 1
	v_add3_u32 v33, v118, v33, s68
	v_bfe_u32 v48, v119, 16, 1
	v_lshrrev_b32_e32 v33, 16, v33
	v_add3_u32 v48, v119, v48, s68
; DI unsigned pk2(float lo, float hi) { return f2bf(lo) | (f2bf(hi) << 16); }
; DI float wave_sum(float v) { v = row16_sum(v); return (rdlane(v, 0) + rdlane(v, 16)) + (rdlane(v, 32) + rdlane(v, 48)); }
; DI void phase_ln(const bf16_t* vin, float* xf, bf16_t* xb, const float* g, const float* b, bool write_f32) {
;     ...
;             const float rstd = rsqrtf(wave_sum(q) * (1.0f / 1024.0f) + 1e-5f);
;             float* row = xf + (size_t)(r0 + k * nw) * D_;
;             bf16_t* rb = xb + (size_t)(r0 + k * nw) * D_;
; #pragma unroll
;             for (int i = 0; i < 4; ++i) {
;                 const f32x4 o = (v[k][i] - mean) * rstd * gv[i] + bv[i];
;                 if (write_f32) *(f32x4*)(row + i * 256 + lane * 4) = o;
;                 u32x2 w; w.x = pk2(o[0], o[1]); w.y = pk2(o[2], o[3]);
;                 *(u32x2*)(rb + i * 256 + lane * 4) = w;
	v_and_or_b32 v118, v48, s39, v33
	v_bfe_u32 v33, v122, 16, 1
	v_add3_u32 v33, v122, v33, s68
	v_bfe_u32 v48, v123, 16, 1
	v_pk_mul_f32 v[116:117], v[116:117], v[46:47] op_sel_hi:[1,0]
	v_lshrrev_b32_e32 v33, 16, v33
	v_add3_u32 v48, v123, v48, s68
	v_add_co_u32_e64 v122, s[0:1], s16, v126
	v_pk_fma_f32 v[116:117], v[4:5], v[116:117], v[12:13]
	v_and_or_b32 v119, v48, s39, v33
	v_addc_co_u32_e64 v123, s[0:1], 0, v127, s[0:1]
	v_bfe_u32 v33, v116, 16, 1
	global_store_dwordx2 v[122:123], v[118:119], off
	v_pk_mul_f32 v[118:119], v[120:121], v[46:47] op_sel_hi:[1,0]
	v_add3_u32 v33, v116, v33, s68
	v_bfe_u32 v48, v117, 16, 1
	v_pk_fma_f32 v[118:119], v[6:7], v[118:119], v[14:15]
	v_lshrrev_b32_e32 v33, 16, v33
	v_add3_u32 v48, v117, v48, s68
	v_and_or_b32 v116, v48, s39, v33
	v_bfe_u32 v33, v118, 16, 1
	v_add3_u32 v33, v118, v33, s68
	v_bfe_u32 v48, v119, 16, 1
	v_pk_mul_f32 v[104:105], v[104:105], v[46:47] op_sel_hi:[1,0]
	v_lshrrev_b32_e32 v33, 16, v33
	v_add3_u32 v48, v119, v48, s68
	v_pk_fma_f32 v[104:105], v[16:17], v[104:105], v[24:25]
	v_and_or_b32 v117, v48, s39, v33
	v_bfe_u32 v33, v104, 16, 1
	v_pk_mul_f32 v[106:107], v[106:107], v[46:47] op_sel_hi:[1,0]
	v_add3_u32 v33, v104, v33, s68
	v_bfe_u32 v48, v105, 16, 1
	v_pk_fma_f32 v[106:107], v[18:19], v[106:107], v[26:27]
	v_lshrrev_b32_e32 v33, 16, v33
	v_add3_u32 v48, v105, v48, s68
	v_and_or_b32 v104, v48, s39, v33
	v_bfe_u32 v33, v106, 16, 1
	v_add3_u32 v33, v106, v33, s68
	v_bfe_u32 v48, v107, 16, 1
	v_pk_mul_f32 v[98:99], v[98:99], v[46:47] op_sel_hi:[1,0]
	v_lshrrev_b32_e32 v33, 16, v33
	v_add3_u32 v48, v107, v48, s68
	v_pk_fma_f32 v[98:99], v[20:21], v[98:99], v[28:29]
	v_and_or_b32 v105, v48, s39, v33
	v_bfe_u32 v33, v98, 16, 1
	v_pk_mul_f32 v[96:97], v[96:97], v[46:47] op_sel_hi:[1,0]
	v_add3_u32 v33, v98, v33, s68
	v_bfe_u32 v46, v99, 16, 1
	v_pk_fma_f32 v[96:97], v[22:23], v[96:97], v[30:31]
	v_lshrrev_b32_e32 v33, 16, v33
	v_add3_u32 v46, v99, v46, s68
	v_and_or_b32 v98, v46, s39, v33
	v_bfe_u32 v33, v96, 16, 1
	v_add3_u32 v33, v96, v33, s68
	v_bfe_u32 v46, v97, 16, 1
	v_lshrrev_b32_e32 v33, 16, v33
	v_add3_u32 v46, v97, v46, s68
	v_and_or_b32 v99, v46, s39, v33
	v_mul_f32_e32 v33, 0x4b800000, v124
	v_cndmask_b32_e32 v33, v124, v33, vcc
	v_rsq_f32_e32 v33, v33
	global_store_dwordx2 v[122:123], v[98:99], off offset:1536
	v_lshl_add_u64 v[96:97], v[42:43], 0, v[136:137]
	global_store_dwordx2 v[122:123], v[116:117], off offset:512
	v_mul_f32_e32 v46, 0x45800000, v33
	v_cndmask_b32_e32 v46, v33, v46, vcc
	v_pk_mul_f32 v[98:99], v[110:111], v[46:47] op_sel_hi:[1,0]
	v_pk_mul_f32 v[100:101], v[114:115], v[46:47] op_sel_hi:[1,0]
	v_pk_fma_f32 v[98:99], v[0:1], v[98:99], v[8:9]
	v_pk_fma_f32 v[100:101], v[2:3], v[100:101], v[10:11]
	v_bfe_u32 v33, v98, 16, 1
	v_add3_u32 v33, v98, v33, s68
	v_bfe_u32 v48, v99, 16, 1
	v_lshrrev_b32_e32 v33, 16, v33
	v_add3_u32 v48, v99, v48, s68
	v_and_or_b32 v98, v48, s39, v33
	v_bfe_u32 v33, v100, 16, 1
	v_add3_u32 v33, v100, v33, s68
	v_bfe_u32 v48, v101, 16, 1
	v_lshrrev_b32_e32 v33, 16, v33
	v_add3_u32 v48, v101, v48, s68
	v_add_co_u32_e32 v96, vcc, s16, v96
	v_and_or_b32 v99, v48, s39, v33
	s_nop 0
	v_addc_co_u32_e32 v97, vcc, 0, v97, vcc
	global_store_dwordx2 v[122:123], v[104:105], off offset:1024
	global_store_dwordx2 v[96:97], v[98:99], off
	v_pk_mul_f32 v[98:99], v[108:109], v[46:47] op_sel_hi:[1,0]
	v_pk_mul_f32 v[100:101], v[112:113], v[46:47] op_sel_hi:[1,0]
	v_pk_fma_f32 v[98:99], v[4:5], v[98:99], v[12:13]
	v_pk_fma_f32 v[100:101], v[6:7], v[100:101], v[14:15]
	v_bfe_u32 v33, v98, 16, 1
	v_add3_u32 v33, v98, v33, s68
	v_bfe_u32 v48, v99, 16, 1
	v_lshrrev_b32_e32 v33, 16, v33
	v_add3_u32 v48, v99, v48, s68
	v_and_or_b32 v98, v48, s39, v33
	v_bfe_u32 v33, v100, 16, 1
	v_add3_u32 v33, v100, v33, s68
	v_bfe_u32 v48, v101, 16, 1
	v_pk_mul_f32 v[86:87], v[86:87], v[46:47] op_sel_hi:[1,0]
	v_lshrrev_b32_e32 v33, 16, v33
	v_add3_u32 v48, v101, v48, s68
	v_pk_fma_f32 v[86:87], v[16:17], v[86:87], v[24:25]
	v_and_or_b32 v99, v48, s39, v33
	v_bfe_u32 v33, v86, 16, 1
	v_pk_mul_f32 v[88:89], v[88:89], v[46:47] op_sel_hi:[1,0]
	v_add3_u32 v33, v86, v33, s68
	v_bfe_u32 v48, v87, 16, 1
	v_pk_fma_f32 v[88:89], v[18:19], v[88:89], v[26:27]
	v_lshrrev_b32_e32 v33, 16, v33
	v_add3_u32 v48, v87, v48, s68
	v_and_or_b32 v86, v48, s39, v33
	v_bfe_u32 v33, v88, 16, 1
	v_add3_u32 v33, v88, v33, s68
	v_bfe_u32 v48, v89, 16, 1
	v_pk_mul_f32 v[80:81], v[80:81], v[46:47] op_sel_hi:[1,0]
	v_lshrrev_b32_e32 v33, 16, v33
	v_add3_u32 v48, v89, v48, s68
	v_pk_fma_f32 v[80:81], v[20:21], v[80:81], v[28:29]
	v_and_or_b32 v87, v48, s39, v33
	v_bfe_u32 v33, v80, 16, 1
	v_pk_mul_f32 v[78:79], v[78:79], v[46:47] op_sel_hi:[1,0]
	v_add3_u32 v33, v80, v33, s68
	v_bfe_u32 v46, v81, 16, 1
	v_pk_fma_f32 v[78:79], v[22:23], v[78:79], v[30:31]
	v_lshrrev_b32_e32 v33, 16, v33
	v_add3_u32 v46, v81, v46, s68
	v_and_or_b32 v80, v46, s39, v33
	v_bfe_u32 v33, v78, 16, 1
	v_add3_u32 v33, v78, v33, s68
	v_bfe_u32 v46, v79, 16, 1
	v_lshrrev_b32_e32 v33, 16, v33
	v_add3_u32 v46, v79, v46, s68
	v_and_or_b32 v81, v46, s39, v33
	global_store_dwordx2 v[96:97], v[80:81], off offset:1536
	v_lshlrev_b32_e32 v79, 16, v93
	v_lshlrev_b32_e32 v78, 16, v92
	v_and_b32_e32 v81, 0xffff0000, v93
	v_and_b32_e32 v80, 0xffff0000, v92
	v_pk_add_f32 v[82:83], v[78:79], v[80:81]
	global_store_dwordx2 v[96:97], v[86:87], off offset:1024
	v_add_f32_e32 v33, v82, v83
	v_lshlrev_b32_e32 v83, 16, v91
	v_lshlrev_b32_e32 v82, 16, v90
	v_pk_add_f32 v[86:87], v[82:83], v[84:85]
	v_add_f32_e32 v66, 0, v33
	v_pk_add_f32 v[86:87], v[86:87], v[86:87] op_sel:[0,1] op_sel_hi:[1,0]
	v_pk_add_f32 v[88:89], v[64:65], v[60:61]
; DI float wave_sum(float v) { v = row16_sum(v); return (rdlane(v, 0) + rdlane(v, 16)) + (rdlane(v, 32) + rdlane(v, 48)); }
; DI void phase_ln(const bf16_t* vin, float* xf, bf16_t* xb, const float* g, const float* b, bool write_f32) {
;     ...
;         for (int k = 0; k < R; ++k) {
;             float s = 0.f;
; #pragma unroll
;             for (int i = 0; i < 4; ++i) s += (v[k][i][0] + v[k][i][1]) + (v[k][i][2] + v[k][i][3]);
;             const float mean = wave_sum(s) * (1.0f / 1024.0f);
;             float q = 0.f;
; #pragma unroll
;             for (int i = 0; i < 4; ++i) { const f32x4 d = v[k][i] - mean; q += (d[0] * d[0] + d[1] * d[1]) + (d[2] * d[2] + d[3] * d[3]); }
;             const float rstd = rsqrtf(wave_sum(q) * (1.0f / 1024.0f) + 1e-5f);
	v_mov_b32_e32 v87, v63
	v_pk_add_f32 v[86:87], v[66:67], v[86:87]
	global_store_dwordx2 v[96:97], v[98:99], off offset:512
	v_pk_add_f32 v[86:87], v[86:87], v[88:89]
	v_lshl_add_u64 v[42:43], v[42:43], 0, s[14:15]
	v_add_f32_e32 v33, v86, v87
	s_nop 1
	v_add_f32_dpp v33, v33, v33 quad_perm:[1,0,3,2] row_mask:0xf bank_mask:0xf bound_ctrl:1
	s_nop 1
	v_add_f32_dpp v33, v33, v33 quad_perm:[2,3,0,1] row_mask:0xf bank_mask:0xf bound_ctrl:1
	s_nop 1
	v_add_f32_dpp v33, v33, v33 row_half_mirror row_mask:0xf bank_mask:0xf bound_ctrl:1
	s_nop 1
	v_add_f32_dpp v33, v33, v33 row_mirror row_mask:0xf bank_mask:0xf bound_ctrl:1
	s_nop 0
	v_readlane_b32 s8, v33, 16
	v_readlane_b32 s9, v33, 48
	v_readlane_b32 s0, v33, 0
	v_readlane_b32 s1, v33, 32
	v_mov_b32_e32 v86, s8
	v_mov_b32_e32 v87, s9
	v_pk_add_f32 v[86:87], s[0:1], v[86:87]
	s_nop 0
	v_add_f32_e32 v33, v86, v87
	v_fmac_f32_e32 v80, 0xba800000, v33
	v_fmac_f32_e32 v81, 0xba800000, v33
	v_fmac_f32_e32 v79, 0xba800000, v33
	v_fmac_f32_e32 v78, 0xba800000, v33
	v_mov_b32_e32 v86, v79
	v_mov_b32_e32 v87, v81
	v_mov_b32_e32 v79, v80
	v_pk_mul_f32 v[88:89], v[86:87], v[86:87]
	v_pk_mul_f32 v[80:81], v[78:79], v[78:79]
	v_fmac_f32_e32 v84, 0xba800000, v33
	v_fmac_f32_e32 v85, 0xba800000, v33
	v_fmac_f32_e32 v83, 0xba800000, v33
	v_pk_mov_b32 v[90:91], v[80:81], v[88:89] op_sel:[1,0]
	v_mov_b32_e32 v81, v89
	v_fmac_f32_e32 v82, 0xba800000, v33
	v_mov_b32_e32 v88, v83
	v_mov_b32_e32 v89, v85
	v_mov_b32_e32 v83, v84
	v_pk_add_f32 v[80:81], v[90:91], v[80:81]
	v_pk_mul_f32 v[90:91], v[88:89], v[88:89]
	v_pk_mul_f32 v[84:85], v[82:83], v[82:83]
	v_fmac_f32_e32 v68, 0xba800000, v33
	v_pk_mov_b32 v[92:93], v[84:85], v[90:91] op_sel:[1,0]
	v_mov_b32_e32 v85, v91
	v_fmac_f32_e32 v69, 0xba800000, v33
	v_fmac_f32_e32 v70, 0xba800000, v33
	v_mul_f32_e32 v46, v68, v68
	v_pk_add_f32 v[84:85], v[92:93], v[84:85]
	v_fmac_f32_e32 v71, 0xba800000, v33
	v_pk_fma_f32 v[90:91], v[68:69], v[68:69], v[46:47] op_sel_hi:[1,1,0]
	v_mul_f32_e32 v46, v70, v70
	v_pk_add_f32 v[80:81], v[80:81], v[80:81] op_sel_hi:[0,1]
	v_pk_add_f32 v[84:85], v[84:85], v[84:85] op_sel_hi:[0,1]
	v_pk_fma_f32 v[92:93], v[70:71], v[70:71], v[46:47] op_sel_hi:[1,1,0]
	v_fmac_f32_e32 v61, 0xba800000, v33
	v_fmac_f32_e32 v65, 0xba800000, v33
	v_fmac_f32_e32 v63, 0xba800000, v33
	v_fmac_f32_e32 v67, 0xba800000, v33
	v_mul_f32_e32 v90, v67, v67
	v_mul_f32_e32 v92, v63, v63
	v_mul_f32_e32 v80, v65, v65
	v_mul_f32_e32 v84, v61, v61
	v_pk_add_f32 v[90:91], v[90:91], v[92:93]
	v_pk_add_f32 v[80:81], v[80:81], v[84:85]
	v_lshlrev_b32_e32 v85, 16, v77
	v_pk_add_f32 v[80:81], v[90:91], v[80:81]
	v_lshlrev_b32_e32 v84, 16, v76
	v_add_f32_e32 v33, v80, v81
	v_and_b32_e32 v77, 0xffff0000, v77
	v_and_b32_e32 v76, 0xffff0000, v76
	v_add_f32_dpp v33, v33, v33 quad_perm:[1,0,3,2] row_mask:0xf bank_mask:0xf bound_ctrl:1
	v_pk_add_f32 v[90:91], v[84:85], v[76:77]
	v_add_f32_e32 v46, v56, v57
	v_add_f32_dpp v33, v33, v33 quad_perm:[2,3,0,1] row_mask:0xf bank_mask:0xf bound_ctrl:1
	v_pk_add_f32 v[96:97], v[50:51], v[46:47]
	v_mov_b32_e32 v62, v67
	v_add_f32_dpp v33, v33, v33 row_half_mirror row_mask:0xf bank_mask:0xf bound_ctrl:1
	v_mov_b32_e32 v60, v65
	s_nop 0
	v_add_f32_dpp v33, v33, v33 row_mirror row_mask:0xf bank_mask:0xf bound_ctrl:1
	s_nop 0
	v_readlane_b32 s0, v33, 0
	v_readlane_b32 s8, v33, 16
	v_readlane_b32 s1, v33, 32
	v_readlane_b32 s9, v33, 48
	v_add_f32_e32 v33, v90, v91
	v_lshlrev_b32_e32 v91, 16, v75
	v_lshlrev_b32_e32 v90, 16, v74
	v_and_b32_e32 v75, 0xffff0000, v75
	v_and_b32_e32 v74, 0xffff0000, v74
	v_pk_add_f32 v[92:93], v[90:91], v[74:75]
	v_add_f32_e32 v52, 0, v33
	v_pk_add_f32 v[92:93], v[92:93], v[92:93] op_sel:[0,1] op_sel_hi:[1,0]
	v_mov_b32_e32 v80, s8
	v_mov_b32_e32 v93, v49
	v_pk_add_f32 v[92:93], v[52:53], v[92:93]
	v_mov_b32_e32 v81, s9
	v_pk_add_f32 v[92:93], v[92:93], v[96:97]
	v_pk_add_f32 v[80:81], s[0:1], v[80:81]
	v_add_f32_e32 v33, v92, v93
	s_nop 1
	v_add_f32_dpp v33, v33, v33 quad_perm:[1,0,3,2] row_mask:0xf bank_mask:0xf bound_ctrl:1
	s_nop 1
	v_add_f32_dpp v33, v33, v33 quad_perm:[2,3,0,1] row_mask:0xf bank_mask:0xf bound_ctrl:1
	s_nop 1
	v_add_f32_dpp v33, v33, v33 row_half_mirror row_mask:0xf bank_mask:0xf bound_ctrl:1
	s_nop 1
	v_add_f32_dpp v33, v33, v33 row_mirror row_mask:0xf bank_mask:0xf bound_ctrl:1
	s_nop 0
	v_readlane_b32 s8, v33, 16
	v_readlane_b32 s9, v33, 48
	v_readlane_b32 s0, v33, 0
	v_readlane_b32 s1, v33, 32
	v_mov_b32_e32 v92, s8
	v_mov_b32_e32 v93, s9
	v_pk_add_f32 v[92:93], s[0:1], v[92:93]
	s_nop 0
	v_add_f32_e32 v33, v92, v93
	v_fmac_f32_e32 v76, 0xba800000, v33
	v_fmac_f32_e32 v77, 0xba800000, v33
	v_fmac_f32_e32 v85, 0xba800000, v33
	v_fmac_f32_e32 v84, 0xba800000, v33
	v_mov_b32_e32 v92, v85
	v_mov_b32_e32 v93, v77
	v_mov_b32_e32 v85, v76
	v_pk_mul_f32 v[96:97], v[92:93], v[92:93]
	v_pk_mul_f32 v[76:77], v[84:85], v[84:85]
	v_fmac_f32_e32 v74, 0xba800000, v33
	v_fmac_f32_e32 v75, 0xba800000, v33
	v_fmac_f32_e32 v91, 0xba800000, v33
	v_pk_mov_b32 v[98:99], v[76:77], v[96:97] op_sel:[1,0]
	v_mov_b32_e32 v77, v97
	v_fmac_f32_e32 v90, 0xba800000, v33
	v_mov_b32_e32 v96, v91
	v_mov_b32_e32 v97, v75
	v_mov_b32_e32 v91, v74
	v_pk_add_f32 v[76:77], v[98:99], v[76:77]
	v_pk_mul_f32 v[98:99], v[96:97], v[96:97]
	v_pk_mul_f32 v[74:75], v[90:91], v[90:91]
	v_fmac_f32_e32 v54, 0xba800000, v33
	v_pk_mov_b32 v[100:101], v[74:75], v[98:99] op_sel:[1,0]
	v_mov_b32_e32 v75, v99
	v_fmac_f32_e32 v55, 0xba800000, v33
	v_fmac_f32_e32 v56, 0xba800000, v33
	v_mul_f32_e32 v46, v54, v54
	v_pk_add_f32 v[74:75], v[100:101], v[74:75]
	v_fmac_f32_e32 v57, 0xba800000, v33
	v_pk_fma_f32 v[98:99], v[54:55], v[54:55], v[46:47] op_sel_hi:[1,1,0]
; DI unsigned pk2(float lo, float hi) { return f2bf(lo) | (f2bf(hi) << 16); }
; DI float wave_sum(float v) { v = row16_sum(v); return (rdlane(v, 0) + rdlane(v, 16)) + (rdlane(v, 32) + rdlane(v, 48)); }
; DI void phase_ln(const bf16_t* vin, float* xf, bf16_t* xb, const float* g, const float* b, bool write_f32) {
;     ...
;             float q = 0.f;
; #pragma unroll
;             for (int i = 0; i < 4; ++i) { const f32x4 d = v[k][i] - mean; q += (d[0] * d[0] + d[1] * d[1]) + (d[2] * d[2] + d[3] * d[3]); }
;             const float rstd = rsqrtf(wave_sum(q) * (1.0f / 1024.0f) + 1e-5f);
;             float* row = xf + (size_t)(r0 + k * nw) * D_;
;             bf16_t* rb = xb + (size_t)(r0 + k * nw) * D_;
; #pragma unroll
;             for (int i = 0; i < 4; ++i) {
;                 const f32x4 o = (v[k][i] - mean) * rstd * gv[i] + bv[i];
;                 if (write_f32) *(f32x4*)(row + i * 256 + lane * 4) = o;
;                 u32x2 w; w.x = pk2(o[0], o[1]); w.y = pk2(o[2], o[3]);
;                 *(u32x2*)(rb + i * 256 + lane * 4) = w;
;             }
;         }
	v_mul_f32_e32 v46, v56, v56
	v_pk_add_f32 v[76:77], v[76:77], v[76:77] op_sel_hi:[0,1]
	v_pk_add_f32 v[74:75], v[74:75], v[74:75] op_sel_hi:[0,1]
	v_pk_fma_f32 v[100:101], v[56:57], v[56:57], v[46:47] op_sel_hi:[1,1,0]
	v_fmac_f32_e32 v47, 0xba800000, v33
	v_fmac_f32_e32 v51, 0xba800000, v33
	v_fmac_f32_e32 v49, 0xba800000, v33
	v_fmac_f32_e32 v53, 0xba800000, v33
	v_mul_f32_e32 v98, v53, v53
	v_mul_f32_e32 v100, v49, v49
	v_mul_f32_e32 v76, v51, v51
	v_mul_f32_e32 v74, v47, v47
	v_pk_add_f32 v[98:99], v[98:99], v[100:101]
	v_pk_add_f32 v[74:75], v[76:77], v[74:75]
	v_mov_b32_e32 v77, v80
	v_pk_add_f32 v[74:75], v[98:99], v[74:75]
	s_nop 0
	v_add_f32_e32 v33, v74, v75
	s_nop 1
	v_add_f32_dpp v33, v33, v33 quad_perm:[1,0,3,2] row_mask:0xf bank_mask:0xf bound_ctrl:1
	s_nop 1
	v_add_f32_dpp v33, v33, v33 quad_perm:[2,3,0,1] row_mask:0xf bank_mask:0xf bound_ctrl:1
	s_nop 1
	v_add_f32_dpp v33, v33, v33 row_half_mirror row_mask:0xf bank_mask:0xf bound_ctrl:1
	s_nop 1
	v_add_f32_dpp v33, v33, v33 row_mirror row_mask:0xf bank_mask:0xf bound_ctrl:1
	s_nop 0
	v_readlane_b32 s8, v33, 16
	v_readlane_b32 s9, v33, 48
	v_readlane_b32 s0, v33, 0
	v_readlane_b32 s1, v33, 32
	v_mov_b32_e32 v74, s8
	v_mov_b32_e32 v75, s9
	v_pk_add_f32 v[74:75], s[0:1], v[74:75]
	s_nop 0
	v_mov_b32_e32 v76, v74
	v_mov_b32_e32 v80, v75
	v_pk_add_f32 v[74:75], v[76:77], v[80:81]
	s_nop 0
	v_pk_fma_f32 v[74:75], v[74:75], s[18:19], v[94:95] op_sel_hi:[1,0,0]
	s_nop 0
	v_mul_f32_e32 v33, 0x4b800000, v75
	v_cmp_gt_f32_e64 s[0:1], s44, v75
	v_cmp_gt_f32_e32 vcc, s44, v74
	s_nop 0
	v_cndmask_b32_e64 v33, v75, v33, s[0:1]
	v_rsq_f32_e32 v33, v33
	s_nop 0
	v_mul_f32_e32 v46, 0x45800000, v33
	v_cndmask_b32_e64 v46, v33, v46, s[0:1]
	v_pk_mul_f32 v[76:77], v[78:79], v[46:47] op_sel_hi:[1,0]
	v_pk_mul_f32 v[78:79], v[86:87], v[46:47] op_sel_hi:[1,0]
	v_pk_fma_f32 v[76:77], v[0:1], v[76:77], v[8:9]
	v_pk_fma_f32 v[78:79], v[2:3], v[78:79], v[10:11]
	v_bfe_u32 v33, v76, 16, 1
	v_add3_u32 v33, v76, v33, s68
	v_bfe_u32 v48, v77, 16, 1
	v_lshrrev_b32_e32 v33, 16, v33
	v_add3_u32 v48, v77, v48, s68
	v_and_or_b32 v76, v48, s39, v33
	v_bfe_u32 v33, v78, 16, 1
	v_add3_u32 v33, v78, v33, s68
	v_bfe_u32 v48, v79, 16, 1
	v_lshrrev_b32_e32 v33, 16, v33
	v_add3_u32 v48, v79, v48, s68
	v_and_or_b32 v77, v48, s39, v33
	global_store_dwordx2 v[72:73], v[76:77], off
	v_pk_mul_f32 v[76:77], v[82:83], v[46:47] op_sel_hi:[1,0]
	v_pk_mul_f32 v[78:79], v[88:89], v[46:47] op_sel_hi:[1,0]
	v_pk_fma_f32 v[76:77], v[4:5], v[76:77], v[12:13]
	v_pk_fma_f32 v[78:79], v[6:7], v[78:79], v[14:15]
	v_bfe_u32 v33, v76, 16, 1
	v_add3_u32 v33, v76, v33, s68
	v_bfe_u32 v48, v77, 16, 1
	v_lshrrev_b32_e32 v33, 16, v33
	v_add3_u32 v48, v77, v48, s68
	v_and_or_b32 v76, v48, s39, v33
	v_bfe_u32 v33, v78, 16, 1
	v_add3_u32 v33, v78, v33, s68
	v_bfe_u32 v48, v79, 16, 1
	v_pk_mul_f32 v[68:69], v[68:69], v[46:47] op_sel_hi:[1,0]
	v_lshrrev_b32_e32 v33, 16, v33
	v_add3_u32 v48, v79, v48, s68
	v_pk_fma_f32 v[68:69], v[16:17], v[68:69], v[24:25]
	v_and_or_b32 v77, v48, s39, v33
	v_bfe_u32 v33, v68, 16, 1
	v_pk_mul_f32 v[70:71], v[70:71], v[46:47] op_sel_hi:[1,0]
	v_add3_u32 v33, v68, v33, s68
	v_bfe_u32 v48, v69, 16, 1
	v_pk_fma_f32 v[70:71], v[18:19], v[70:71], v[26:27]
	v_lshrrev_b32_e32 v33, 16, v33
	v_add3_u32 v48, v69, v48, s68
	v_and_or_b32 v68, v48, s39, v33
	v_bfe_u32 v33, v70, 16, 1
	v_add3_u32 v33, v70, v33, s68
	v_bfe_u32 v48, v71, 16, 1
	v_pk_mul_f32 v[62:63], v[62:63], v[46:47] op_sel_hi:[1,0]
	v_lshrrev_b32_e32 v33, 16, v33
	v_add3_u32 v48, v71, v48, s68
	v_pk_fma_f32 v[62:63], v[20:21], v[62:63], v[28:29]
; DI unsigned pk2(float lo, float hi) { return f2bf(lo) | (f2bf(hi) << 16); }
; DI void phase_ln(const bf16_t* vin, float* xf, bf16_t* xb, const float* g, const float* b, bool write_f32) {
;     ...
;             for (int i = 0; i < 4; ++i) {
;                 const f32x4 o = (v[k][i] - mean) * rstd * gv[i] + bv[i];
;                 if (write_f32) *(f32x4*)(row + i * 256 + lane * 4) = o;
;                 u32x2 w; w.x = pk2(o[0], o[1]); w.y = pk2(o[2], o[3]);
;                 *(u32x2*)(rb + i * 256 + lane * 4) = w;
;             }
;         }
	v_and_or_b32 v69, v48, s39, v33
	v_bfe_u32 v33, v62, 16, 1
	v_pk_mul_f32 v[60:61], v[60:61], v[46:47] op_sel_hi:[1,0]
	v_add3_u32 v33, v62, v33, s68
	v_bfe_u32 v46, v63, 16, 1
	v_pk_fma_f32 v[60:61], v[22:23], v[60:61], v[30:31]
	v_lshrrev_b32_e32 v33, 16, v33
	v_add3_u32 v46, v63, v46, s68
	v_and_or_b32 v62, v46, s39, v33
	v_bfe_u32 v33, v60, 16, 1
	v_add3_u32 v33, v60, v33, s68
	v_bfe_u32 v46, v61, 16, 1
	v_lshrrev_b32_e32 v33, 16, v33
	v_add3_u32 v46, v61, v46, s68
	v_and_or_b32 v63, v46, s39, v33
	v_mul_f32_e32 v33, 0x4b800000, v74
	v_cndmask_b32_e32 v33, v74, v33, vcc
	v_rsq_f32_e32 v33, v33
	global_store_dwordx2 v[72:73], v[62:63], off offset:1536
	v_mov_b32_e32 v48, v53
	s_mov_b32 s0, 0xffff
	v_mul_f32_e32 v46, 0x45800000, v33
	v_cndmask_b32_e32 v50, v33, v46, vcc
	v_pk_mul_f32 v[60:61], v[84:85], v[50:51] op_sel_hi:[1,0]
	v_pk_mul_f32 v[62:63], v[92:93], v[50:51] op_sel_hi:[1,0]
	v_pk_fma_f32 v[60:61], v[0:1], v[60:61], v[8:9]
	v_pk_fma_f32 v[62:63], v[2:3], v[62:63], v[10:11]
	v_bfe_u32 v33, v60, 16, 1
	v_add3_u32 v33, v60, v33, s68
	v_bfe_u32 v46, v61, 16, 1
	v_lshrrev_b32_e32 v33, 16, v33
	v_add3_u32 v46, v61, v46, s68
	v_and_or_b32 v60, v46, s39, v33
	v_bfe_u32 v33, v62, 16, 1
	v_add3_u32 v33, v62, v33, s68
	v_bfe_u32 v46, v63, 16, 1
	v_lshrrev_b32_e32 v33, 16, v33
	v_add3_u32 v46, v63, v46, s68
	v_and_or_b32 v61, v46, s39, v33
	global_store_dwordx2 v[58:59], v[60:61], off
	v_pk_mul_f32 v[60:61], v[90:91], v[50:51] op_sel_hi:[1,0]
	v_pk_mul_f32 v[62:63], v[96:97], v[50:51] op_sel_hi:[1,0]
	v_pk_fma_f32 v[60:61], v[4:5], v[60:61], v[12:13]
	v_pk_fma_f32 v[62:63], v[6:7], v[62:63], v[14:15]
	v_bfe_u32 v33, v60, 16, 1
	v_add3_u32 v33, v60, v33, s68
	v_bfe_u32 v46, v61, 16, 1
	v_lshrrev_b32_e32 v33, 16, v33
	v_add3_u32 v46, v61, v46, s68
	v_and_or_b32 v60, v46, s39, v33
	v_bfe_u32 v33, v62, 16, 1
	v_add3_u32 v33, v62, v33, s68
	v_bfe_u32 v46, v63, 16, 1
	v_pk_mul_f32 v[54:55], v[54:55], v[50:51] op_sel_hi:[1,0]
	v_lshrrev_b32_e32 v33, 16, v33
	v_add3_u32 v46, v63, v46, s68
	v_pk_fma_f32 v[54:55], v[16:17], v[54:55], v[24:25]
	v_and_or_b32 v61, v46, s39, v33
	v_bfe_u32 v33, v54, 16, 1
	v_pk_mul_f32 v[56:57], v[56:57], v[50:51] op_sel_hi:[1,0]
	v_add3_u32 v33, v54, v33, s68
	v_bfe_u32 v46, v55, 16, 1
	v_pk_fma_f32 v[56:57], v[18:19], v[56:57], v[26:27]
	v_lshrrev_b32_e32 v33, 16, v33
	v_add3_u32 v46, v55, v46, s68
	v_and_or_b32 v54, v46, s39, v33
	v_bfe_u32 v33, v56, 16, 1
	v_add3_u32 v33, v56, v33, s68
	v_bfe_u32 v46, v57, 16, 1
	v_pk_mul_f32 v[48:49], v[48:49], v[50:51] op_sel_hi:[1,0]
	v_lshrrev_b32_e32 v33, 16, v33
	v_add3_u32 v46, v57, v46, s68
	v_pk_fma_f32 v[48:49], v[20:21], v[48:49], v[28:29]
	v_and_or_b32 v55, v46, s39, v33
	v_mov_b32_e32 v46, v51
	v_bfe_u32 v33, v48, 16, 1
	v_pk_mul_f32 v[46:47], v[46:47], v[50:51] op_sel_hi:[1,0]
	v_add3_u32 v33, v48, v33, s68
	v_bfe_u32 v48, v49, 16, 1
	v_pk_fma_f32 v[46:47], v[22:23], v[46:47], v[30:31]
	v_lshrrev_b32_e32 v33, 16, v33
	v_add3_u32 v48, v49, v48, s68
	v_and_or_b32 v48, v48, s39, v33
	v_bfe_u32 v33, v46, 16, 1
	v_add3_u32 v33, v46, v33, s68
	v_bfe_u32 v46, v47, 16, 1
	v_lshrrev_b32_e32 v33, 16, v33
	v_add3_u32 v46, v47, v46, s68
	v_cmp_lt_i32_e32 vcc, s0, v32
	v_and_or_b32 v49, v46, s39, v33
	s_or_b64 s[6:7], vcc, s[6:7]
	global_store_dwordx2 v[72:73], v[76:77], off offset:512
	global_store_dwordx2 v[72:73], v[68:69], off offset:1024
	global_store_dwordx2 v[58:59], v[60:61], off offset:512
	global_store_dwordx2 v[58:59], v[54:55], off offset:1024
	global_store_dwordx2 v[58:59], v[48:49], off offset:1536
	s_andn2_b64 exec, exec, s[6:7]
	s_cbranch_execnz .LBB0_568
